# sample-attention loop: packed fp32 muls on the MFMA accumulators split into scalar pairs
# speedup vs baseline: 1.0027x; 1.0027x over previous
; __device__ __forceinline__ unsigned pk2(float lo, float hi) { const f32x2_ v = {lo, hi}; return __builtin_bit_cast(unsigned, __builtin_convertvector(v, bf16x2_)); }
; __device__ __forceinline__ void attn_sample_unit(const PP P, LAS unsigned char* lds, int b, int h) {
;     ...
;     for (int kb = kb0; kb < kb1; ++kb) {
;         f32x4 s[2]; int kof[2];
; #pragma unroll
;         for (int sub = 0; sub < 2; ++sub) { const int key0 = kb * 32 + sub * 16; const bool valid = key0 < nkeys; kof[sub] = (valid && key0 >= 2048) ? 65536 + b * 16 + (key0 - 2048) : b * 2048 + (valid ? key0 : 0);
;             const size_t kr = (size_t)keybase + kof[sub] + fr;
;             const bf16x8 a0 = *(const bf16x8*)(KN + kr * 512 + h * 64 + fq * 8), a1 = *(const bf16x8*)(KN + kr * 512 + h * 64 + 32 + fq * 8), a2 = *(const bf16x8*)(KPEB + kr * 32 + fq * 8);
;             f32x4 acc = {0.f, 0.f, 0.f, 0.f}; acc = mfma16(a0, Qb[0], acc); acc = mfma16(a1, Qb[1], acc); acc = mfma16(a2, Qb[2], acc);
;             if (!valid) acc = (f32x4){-INFINITY, -INFINITY, -INFINITY, -INFINITY};
;             s[sub] = acc; }
;         float mx = fmaxf(fmaxf(fmaxf(s[0][0], s[0][1]), fmaxf(s[0][2], s[0][3])), fmaxf(fmaxf(s[1][0], s[1][1]), fmaxf(s[1][2], s[1][3])));
;         mx = fmaxf(mx, xor16_get(mx)); mx = xor32_max(mx);
;         const float mnew = fmaxf(m, mx); const float alpha = __builtin_amdgcn_exp2f(m - mnew); m = mnew;
;         float p[8]; float ps = 0.f;
; #pragma unroll
;         for (int j = 0; j < 4; ++j) { p[j] = __builtin_amdgcn_exp2f(s[0][j] - mnew); p[4 + j] = __builtin_amdgcn_exp2f(s[1][j] - mnew); ps += p[j] + p[4 + j]; }
;         lsum = lsum * alpha + ps;
;         u32x4 pw; pw.x = pk2(p[0], p[1]); pw.y = pk2(p[2], p[3]); pw.z = pk2(p[4], p[5]); pw.w = pk2(p[6], p[7]);
;         const bf16x8 Pb = __builtin_bit_cast(bf16x8, pw);
; #pragma unroll
;         for (int nt = 0; nt < 4; ++nt) { const bf16* vrow = VT + (size_t)(h * 64 + 16 * nt + fr) * NK + keybase + fq * 4;
;             const s16x4 a = *(const s16x4*)(vrow + kof[0]), c = *(const s16x4*)(vrow + kof[1]);
;             bf16x8 va; va[0] = a[0]; va[1] = a[1]; va[2] = a[2]; va[3] = a[3]; va[4] = c[0]; va[5] = c[1]; va[6] = c[2]; va[7] = c[3];
;             O[nt] = mfma16(va, Pb, O[nt] * alpha); }
;     }
.LBB0_54:
	v_add_u32_e32 v200, 16, v51
	v_cmp_gt_i32_e32 vcc, 0x810, v200
	s_nop 1
	v_cndmask_b32_e32 v200, 0, v200, vcc
	v_add_u32_e32 v228, s36, v200
	v_ashrrev_i32_e32 v229, 31, v228
	v_lshl_add_u64 v[230:231], v[228:229], 0, v[108:109]
	v_lshlrev_b64 v[232:233], 10, v[230:231]
	v_lshl_add_u64 v[232:233], v[48:49], 0, v[232:233]
	global_load_dwordx4 v[200:203], v[232:233], off
	global_load_dwordx4 v[204:207], v[232:233], off offset:64
	v_lshlrev_b64 v[230:231], 6, v[230:231]
	v_lshl_add_u64 v[230:231], v[110:111], 0, v[230:231]
	global_load_dwordx4 v[208:211], v[230:231], off
	v_lshlrev_b64 v[234:235], 1, v[228:229]
	s_movk_i32 s14, 0x41
	v_cmp_gt_i32_e32 vcc, s14, v59
	v_cmp_eq_u32_e64 s[14:15], 64, v59
	v_mov_b32_e32 v31, s35
	v_cndmask_b32_e32 v30, 0, v51, vcc
	v_add_u32_e32 v30, s36, v30
	v_cndmask_b32_e64 v60, v30, v31, s[14:15]
	v_ashrrev_i32_e32 v61, 31, v60
	v_lshl_add_u64 v[52:53], v[60:61], 0, v[108:109]
	v_lshlrev_b64 v[30:31], 10, v[52:53]
	v_lshl_add_u64 v[34:35], v[48:49], 0, v[30:31]
	global_load_dwordx4 v[30:33], v[34:35], off
	s_nop 0
	global_load_dwordx4 v[34:37], v[34:35], off offset:64
	v_lshlrev_b64 v[52:53], 6, v[52:53]
	v_lshl_add_u64 v[52:53], v[110:111], 0, v[52:53]
	global_load_dwordx4 v[52:55], v[52:53], off
	s_movk_i32 s14, 0x810
	v_mov_b32_e32 v62, v24
	v_mov_b32_e32 v24, v50
	v_lshlrev_b64 v[60:61], 1, v[60:61]
	v_lshl_add_u64 v[236:237], v[40:41], 0, v[60:61]
	global_load_dwordx2 v[212:213], v[236:237], off
	v_lshl_add_u64 v[238:239], v[40:41], 0, v[234:235]
	global_load_dwordx2 v[214:215], v[238:239], off
	v_lshl_add_u64 v[236:237], v[42:43], 0, v[60:61]
	global_load_dwordx2 v[216:217], v[236:237], off
	v_lshl_add_u64 v[238:239], v[42:43], 0, v[234:235]
	global_load_dwordx2 v[218:219], v[238:239], off
	v_lshl_add_u64 v[236:237], v[44:45], 0, v[60:61]
	global_load_dwordx2 v[220:221], v[236:237], off
	v_lshl_add_u64 v[238:239], v[44:45], 0, v[234:235]
	global_load_dwordx2 v[222:223], v[238:239], off
	v_lshl_add_u64 v[236:237], v[46:47], 0, v[60:61]
	global_load_dwordx2 v[224:225], v[236:237], off
	v_lshl_add_u64 v[238:239], v[46:47], 0, v[234:235]
	global_load_dwordx2 v[226:227], v[238:239], off
	s_waitcnt vmcnt(10)
	v_mfma_f32_16x16x32_bf16 v[30:33], v[30:33], v[26:29], 0
	s_waitcnt vmcnt(9)
	v_mfma_f32_16x16x32_bf16 v[30:33], v[34:37], v[20:23], v[30:33]
	s_waitcnt vmcnt(8)
	v_mfma_f32_16x16x32_bf16 v[30:33], v[52:55], v[16:19], v[30:33]
	s_nop 7
	v_cndmask_b32_e32 v58, v166, v30, vcc
	v_add_u32_e32 v30, 16, v51
	v_cndmask_b32_e32 v56, v166, v32, vcc
	v_cndmask_b32_e32 v57, v166, v33, vcc
	v_cndmask_b32_e32 v63, v166, v31, vcc
	v_cmp_gt_i32_e32 vcc, s14, v30
	v_max_f32_e32 v50, v56, v56
	v_add_u32_e32 v51, 32, v51
	v_cndmask_b32_e32 v30, 0, v30, vcc
	v_add_u32_e32 v36, s36, v30
	v_ashrrev_i32_e32 v37, 31, v36
	v_lshl_add_u64 v[34:35], v[36:37], 0, v[108:109]
	v_lshlrev_b64 v[30:31], 10, v[34:35]
	v_lshl_add_u64 v[52:53], v[48:49], 0, v[30:31]
	v_lshlrev_b64 v[34:35], 6, v[34:35]
	v_lshl_add_u64 v[34:35], v[110:111], 0, v[34:35]
	v_max_f32_e32 v34, v63, v63
	v_max_f32_e32 v35, v58, v58
	v_max_f32_e32 v34, v35, v34
	v_max_f32_e32 v35, v57, v57
	v_max_f32_e32 v35, v50, v35
	s_waitcnt vmcnt(8)
	v_mfma_f32_16x16x32_bf16 v[30:33], v[200:203], v[26:29], 0
	v_mfma_f32_16x16x32_bf16 v[30:33], v[204:207], v[20:23], v[30:33]
	v_mfma_f32_16x16x32_bf16 v[30:33], v[208:211], v[16:19], v[30:33]
	s_nop 7
	v_cndmask_b32_e32 v32, v166, v32, vcc
	v_cndmask_b32_e32 v33, v166, v33, vcc
	v_max_f32_e32 v50, v33, v33
	v_max_f32_e32 v52, v32, v32
	v_cndmask_b32_e32 v31, v166, v31, vcc
	v_cndmask_b32_e32 v30, v166, v30, vcc
	v_max_f32_e32 v50, v52, v50
	v_max3_f32 v50, v30, v31, v50
	v_max3_f32 v34, v34, v35, v50
	ds_swizzle_b32 v35, v34 offset:swizzle(SWAP,16)
	s_waitcnt lgkmcnt(0)
	v_max_f32_e32 v35, v35, v35
	v_max_f32_e32 v34, v34, v35
	v_mov_b32_e32 v35, v34
	s_nop 1
	v_permlane32_swap_b32_e32 v34, v35
	v_max3_f32 v50, v24, v34, v35
	v_sub_f32_e32 v34, v24, v50
	v_sub_f32_e32 v24, v58, v50
	v_exp_f32_e32 v35, v24
	v_sub_f32_e32 v24, v30, v50
	v_sub_f32_e32 v30, v31, v50
	v_exp_f32_e32 v64, v24
	v_sub_f32_e32 v24, v63, v50
	v_exp_f32_e32 v52, v30
	v_exp_f32_e32 v24, v24
	v_sub_f32_e32 v30, v56, v50
	v_exp_f32_e32 v31, v30
	v_sub_f32_e32 v30, v32, v50
	v_exp_f32_e32 v63, v30
	v_sub_f32_e32 v30, v57, v50
	v_add_f32_e32 v53, v64, v35
	v_exp_f32_e32 v56, v30
	v_sub_f32_e32 v30, v33, v50
	v_cvt_pk_bf16_f32 v32, v64, v52
	v_lshlrev_b64 v[64:65], 1, v[36:37]
	v_exp_f32_e32 v54, v30
	v_exp_f32_e32 v58, v34
	v_cvt_pk_bf16_f32 v30, v35, v24
	v_add_f32_e32 v55, v63, v31
	v_cvt_pk_bf16_f32 v31, v31, v56
	v_cvt_pk_bf16_f32 v33, v63, v54
	v_mul_f32_e32 v14, v58, v14
	v_mul_f32_e32 v15, v58, v15
	v_mul_f32_e32 v12, v58, v12
	v_mul_f32_e32 v13, v58, v13
	v_mul_f32_e32 v10, v58, v10
	v_mul_f32_e32 v11, v58, v11
	v_mul_f32_e32 v8, v58, v8
	v_mul_f32_e32 v9, v58, v9
	v_mul_f32_e32 v6, v58, v6
	v_mul_f32_e32 v7, v58, v7
	v_mul_f32_e32 v4, v58, v4
	v_mul_f32_e32 v5, v58, v5
	v_mul_f32_e32 v2, v58, v2
	v_mul_f32_e32 v3, v58, v3
	v_mul_f32_e32 v0, v58, v0
	v_mul_f32_e32 v1, v58, v1
	v_add_u32_e32 v59, 1, v59
	v_cmp_ge_i32_e32 vcc, v59, v149
	s_or_b64 s[26:27], vcc, s[26:27]
	s_waitcnt vmcnt(6)
	v_mfma_f32_16x16x32_bf16 v[12:15], v[212:215], v[30:33], v[12:15]
	s_waitcnt vmcnt(4)
	v_mfma_f32_16x16x32_bf16 v[8:11], v[216:219], v[30:33], v[8:11]
	s_waitcnt vmcnt(2)
	v_mfma_f32_16x16x32_bf16 v[4:7], v[220:223], v[30:33], v[4:7]
	s_waitcnt vmcnt(0)
	v_mfma_f32_16x16x32_bf16 v[0:3], v[224:227], v[30:33], v[0:3]
	v_add_f32_e64 v30, v52, v24
	v_add_f32_e64 v31, v53, v25
	v_pk_add_f32 v[30:31], v[30:31], v[30:31] op_sel_hi:[0,1]
	v_mov_b32_e32 v57, v31
	v_pk_add_f32 v[30:31], v[54:55], v[56:57]
	s_nop 0
	v_add_f32_e32 v24, v30, v31
	v_fmac_f32_e32 v24, v62, v58
	s_andn2_b64 exec, exec, s[26:27]
	s_cbranch_execnz .LBB0_54
	s_or_b64 exec, exec, s[26:27]
